# P1 plain epilogue: 16-byte pieces moved by ds_bpermute so each lane quad stores 64 contiguous bytes of one row (saddr stores); on top of v66
# speedup vs baseline: 1.0012x; 1.0012x over previous
;     __device__ __forceinline__ void operator()(const f32x4 (&acc)[2][2][4][2], const Unit& u, int wr, int wc, int fr, int fq) const {
;         const int row0 = u.pm * BM + wr * 64 + fr, col0 = u.pn * BM + wc * 32 + 8 * fq;
;         if (u.pn >= qn_lo && u.pn < qn_hi) {
;     ...
; #pragma unroll
;         for (int ai = 0; ai < 2; ++ai)
; #pragma unroll
;             for (int m = 0; m < 4; ++m) { bf16_t* rowp = O + (size_t)(row0 + ai * HALF + m * 16) * ldc + col0;
.LBB0_183:
	s_mul_i32 s20, s30, 0xb00000
	s_lshl_b32 s21, s6, 9
	s_add_u32 s20, s20, s21
	s_addc_u32 s21, 0, 0
	s_add_u32 s20, s20, s86
	s_addc_u32 s21, s21, s87
	v_lshl_add_u32 v184, s30, 8, v158
	s_and_b32 s7, s6, -16
	v_lshl_or_b32 v146, s6, 8, v169
	s_mov_b64 s[30:31], -1
	s_cmp_eq_u32 s7, 32
	v_or_b32_e32 v183, 16, v184
	v_or_b32_e32 v182, 32, v184
	v_or_b32_e32 v181, 48, v184
	v_add_u32_e32 v180, 0x80, v184
	v_add_u32_e32 v179, 0x90, v184
	v_add_u32_e32 v178, 0xa0, v184
	v_add_u32_e32 v177, 0xb0, v184
	s_cbranch_scc0 .LBB0_186
	s_andn2_b64 vcc, exec, s[30:31]
	s_cbranch_vccz .LBB0_187

; __device__ __forceinline__ unsigned cvt_pk_bf16(float lo, float hi) { unsigned r; asm volatile("v_cvt_pk_bf16_f32 %0, %1, %2" : "=v"(r) : "v"(lo), "v"(hi)); return r; }
;     __device__ __forceinline__ void operator()(const f32x4 (&acc)[2][2][4][2], const Unit& u, int wr, int wc, int fr, int fq) const {
;     ...
; #pragma unroll
;         for (int ai = 0; ai < 2; ++ai)
; #pragma unroll
;             for (int m = 0; m < 4; ++m) { bf16_t* rowp = O + (size_t)(row0 + ai * HALF + m * 16) * ldc + col0;
; #pragma unroll
;                 for (int bj = 0; bj < 2; ++bj) { const f32x4 v0 = acc[ai][bj][m][0], v1 = acc[ai][bj][m][1];
;                     u32x4 w; w.x = cvt_pk_bf16(v0[0], v0[1]); w.y = cvt_pk_bf16(v0[2], v0[3]); w.z = cvt_pk_bf16(v1[0], v1[1]); w.w = cvt_pk_bf16(v1[2], v1[3]);
;                     *(u32x4*)(rowp + bj * HALF) = w; } }
.Lbp_epi:
	v_mbcnt_lo_u32_b32 v236, -1, 0
	v_mbcnt_hi_u32_b32 v236, -1, v236
	v_and_b32_e32 v237, 3, v236
	v_lshrrev_b32_e32 v236, 2, v236
	v_lshl_add_u32 v252, v237, 4, v236
	v_lshlrev_b32_e32 v252, 2, v252
	v_and_b32_e32 v253, 64, v158
	v_add_u32_e32 v253, v253, v236
	v_mul_u32_u24_e32 v253, 0xb000, v253
	v_lshrrev_b32_e32 v236, 5, v169
	v_lshl_add_u32 v253, v236, 6, v253
	v_lshl_add_u32 v253, v237, 4, v253
	v_cvt_pk_bf16_f32 v126, v126, v127
	v_cvt_pk_bf16_f32 v127, v128, v129
	v_cvt_pk_bf16_f32 v128, v122, v123
	v_cvt_pk_bf16_f32 v129, v124, v125
	v_cvt_pk_bf16_f32 v118, v118, v119
	v_cvt_pk_bf16_f32 v119, v120, v121
	v_cvt_pk_bf16_f32 v120, v114, v115
	v_cvt_pk_bf16_f32 v121, v116, v117
	ds_bpermute_b32 v236, v252, v126
	ds_bpermute_b32 v237, v252, v127
	ds_bpermute_b32 v238, v252, v128
	ds_bpermute_b32 v239, v252, v129
	ds_bpermute_b32 v240, v252, v118
	ds_bpermute_b32 v241, v252, v119
	ds_bpermute_b32 v242, v252, v120
	ds_bpermute_b32 v243, v252, v121
	v_cvt_pk_bf16_f32 v110, v110, v111
	v_cvt_pk_bf16_f32 v111, v112, v113
	v_cvt_pk_bf16_f32 v112, v106, v107
	v_cvt_pk_bf16_f32 v113, v108, v109
	v_cvt_pk_bf16_f32 v102, v102, v103
	v_cvt_pk_bf16_f32 v103, v104, v105
	v_cvt_pk_bf16_f32 v104, v98, v99
	v_cvt_pk_bf16_f32 v105, v100, v101
	ds_bpermute_b32 v244, v252, v110
	ds_bpermute_b32 v245, v252, v111
	ds_bpermute_b32 v246, v252, v112
	ds_bpermute_b32 v247, v252, v113
	ds_bpermute_b32 v248, v252, v102
	ds_bpermute_b32 v249, v252, v103
	ds_bpermute_b32 v250, v252, v104
	ds_bpermute_b32 v251, v252, v105
	s_waitcnt lgkmcnt(8)
	s_mov_b64 s[22:23], s[20:21]
	global_store_dwordx4 v253, v[236:239], s[22:23]
	global_store_dwordx4 v253, v[240:243], s[22:23] offset:256
	v_cvt_pk_bf16_f32 v94, v94, v95
	v_cvt_pk_bf16_f32 v95, v96, v97
	v_cvt_pk_bf16_f32 v96, v90, v91
	v_cvt_pk_bf16_f32 v97, v92, v93
	v_cvt_pk_bf16_f32 v86, v86, v87
	v_cvt_pk_bf16_f32 v87, v88, v89
	v_cvt_pk_bf16_f32 v88, v82, v83
	v_cvt_pk_bf16_f32 v89, v84, v85
	ds_bpermute_b32 v236, v252, v94
	ds_bpermute_b32 v237, v252, v95
	ds_bpermute_b32 v238, v252, v96
	ds_bpermute_b32 v239, v252, v97
	ds_bpermute_b32 v240, v252, v86
	ds_bpermute_b32 v241, v252, v87
	ds_bpermute_b32 v242, v252, v88
	ds_bpermute_b32 v243, v252, v89
	s_waitcnt lgkmcnt(8)
	s_add_u32 s22, s20, 0xb0000
	s_addc_u32 s23, s21, 0
	global_store_dwordx4 v253, v[244:247], s[22:23]
	global_store_dwordx4 v253, v[248:251], s[22:23] offset:256
	v_cvt_pk_bf16_f32 v78, v78, v79
	v_cvt_pk_bf16_f32 v79, v80, v81
	v_cvt_pk_bf16_f32 v80, v74, v75
	v_cvt_pk_bf16_f32 v81, v76, v77
	v_cvt_pk_bf16_f32 v70, v70, v71
	v_cvt_pk_bf16_f32 v71, v72, v73
	v_cvt_pk_bf16_f32 v72, v66, v67
	v_cvt_pk_bf16_f32 v73, v68, v69
	ds_bpermute_b32 v244, v252, v78
	ds_bpermute_b32 v245, v252, v79
	ds_bpermute_b32 v246, v252, v80
	ds_bpermute_b32 v247, v252, v81
	ds_bpermute_b32 v248, v252, v70
	ds_bpermute_b32 v249, v252, v71
	ds_bpermute_b32 v250, v252, v72
	ds_bpermute_b32 v251, v252, v73
	s_waitcnt lgkmcnt(8)
	s_add_u32 s22, s20, 0x160000
	s_addc_u32 s23, s21, 0
	global_store_dwordx4 v253, v[236:239], s[22:23]
	global_store_dwordx4 v253, v[240:243], s[22:23] offset:256
	v_cvt_pk_bf16_f32 v62, v62, v63
	v_cvt_pk_bf16_f32 v63, v64, v65
	v_cvt_pk_bf16_f32 v64, v58, v59
	v_cvt_pk_bf16_f32 v65, v60, v61
	v_cvt_pk_bf16_f32 v54, v54, v55
	v_cvt_pk_bf16_f32 v55, v56, v57
	v_cvt_pk_bf16_f32 v56, v50, v51
	v_cvt_pk_bf16_f32 v57, v52, v53
	ds_bpermute_b32 v236, v252, v62
	ds_bpermute_b32 v237, v252, v63
	ds_bpermute_b32 v238, v252, v64
	ds_bpermute_b32 v239, v252, v65
	ds_bpermute_b32 v240, v252, v54
	ds_bpermute_b32 v241, v252, v55
	ds_bpermute_b32 v242, v252, v56
	ds_bpermute_b32 v243, v252, v57
	s_waitcnt lgkmcnt(8)
	s_add_u32 s22, s20, 0x210000
	s_addc_u32 s23, s21, 0
	global_store_dwordx4 v253, v[244:247], s[22:23]
	global_store_dwordx4 v253, v[248:251], s[22:23] offset:256
	v_cvt_pk_bf16_f32 v46, v46, v47
	v_cvt_pk_bf16_f32 v47, v48, v49
	v_cvt_pk_bf16_f32 v48, v42, v43
	v_cvt_pk_bf16_f32 v49, v44, v45
	v_cvt_pk_bf16_f32 v38, v38, v39
	v_cvt_pk_bf16_f32 v39, v40, v41
	v_cvt_pk_bf16_f32 v40, v34, v35
	v_cvt_pk_bf16_f32 v41, v36, v37
	ds_bpermute_b32 v244, v252, v46
	ds_bpermute_b32 v245, v252, v47
	ds_bpermute_b32 v246, v252, v48
	ds_bpermute_b32 v247, v252, v49
	ds_bpermute_b32 v248, v252, v38
	ds_bpermute_b32 v249, v252, v39
	ds_bpermute_b32 v250, v252, v40
	ds_bpermute_b32 v251, v252, v41
	s_waitcnt lgkmcnt(8)
	s_add_u32 s22, s20, 0x580000
	s_addc_u32 s23, s21, 0
	global_store_dwordx4 v253, v[236:239], s[22:23]
	global_store_dwordx4 v253, v[240:243], s[22:23] offset:256
	v_cvt_pk_bf16_f32 v30, v30, v31
	v_cvt_pk_bf16_f32 v31, v32, v33
	v_cvt_pk_bf16_f32 v32, v26, v27
	v_cvt_pk_bf16_f32 v33, v28, v29
	v_cvt_pk_bf16_f32 v22, v22, v23
	v_cvt_pk_bf16_f32 v23, v24, v25
	v_cvt_pk_bf16_f32 v24, v18, v19
	v_cvt_pk_bf16_f32 v25, v20, v21
	ds_bpermute_b32 v236, v252, v30
	ds_bpermute_b32 v237, v252, v31
	ds_bpermute_b32 v238, v252, v32
	ds_bpermute_b32 v239, v252, v33
	ds_bpermute_b32 v240, v252, v22
	ds_bpermute_b32 v241, v252, v23
	ds_bpermute_b32 v242, v252, v24
	ds_bpermute_b32 v243, v252, v25
	s_waitcnt lgkmcnt(8)
	s_add_u32 s22, s20, 0x630000
	s_addc_u32 s23, s21, 0
	global_store_dwordx4 v253, v[244:247], s[22:23]
	global_store_dwordx4 v253, v[248:251], s[22:23] offset:256
	v_cvt_pk_bf16_f32 v14, v14, v15
	v_cvt_pk_bf16_f32 v15, v16, v17
	v_cvt_pk_bf16_f32 v16, v10, v11
	v_cvt_pk_bf16_f32 v17, v12, v13
	v_cvt_pk_bf16_f32 v6, v6, v7
	v_cvt_pk_bf16_f32 v7, v8, v9
	v_cvt_pk_bf16_f32 v8, v2, v3
	v_cvt_pk_bf16_f32 v9, v4, v5
	ds_bpermute_b32 v244, v252, v14
	ds_bpermute_b32 v245, v252, v15
	ds_bpermute_b32 v246, v252, v16
	ds_bpermute_b32 v247, v252, v17
	ds_bpermute_b32 v248, v252, v6
	ds_bpermute_b32 v249, v252, v7
	ds_bpermute_b32 v250, v252, v8
	ds_bpermute_b32 v251, v252, v9
	s_waitcnt lgkmcnt(8)
	s_add_u32 s22, s20, 0x6e0000
	s_addc_u32 s23, s21, 0
	global_store_dwordx4 v253, v[236:239], s[22:23]
	global_store_dwordx4 v253, v[240:243], s[22:23] offset:256
	s_waitcnt lgkmcnt(0)
	s_add_u32 s22, s20, 0x790000
	s_addc_u32 s23, s21, 0
	global_store_dwordx4 v253, v[244:247], s[22:23]
	global_store_dwordx4 v253, v[248:251], s[22:23] offset:256
	s_andn2_b64 vcc, exec, s[4:5]
	s_mov_b64 s[4:5], -1
	s_cbranch_vccnz .LBB0_176
	s_branch .LBB0_220
; __device__ __forceinline__ unsigned cvt_pk_bf16(float lo, float hi) { unsigned r; asm volatile("v_cvt_pk_bf16_f32 %0, %1, %2" : "=v"(r) : "v"(lo), "v"(hi)); return r; }
;     __device__ __forceinline__ void operator()(const f32x4 (&acc)[2][2][4][2], const Unit& u, int wr, int wc, int fr, int fq) const {
;     ...
; #pragma unroll
;         for (int ai = 0; ai < 2; ++ai)
; #pragma unroll
;             for (int m = 0; m < 4; ++m) { bf16_t* rowp = O + (size_t)(row0 + ai * HALF + m * 16) * ldc + col0;
; #pragma unroll
;                 for (int bj = 0; bj < 2; ++bj) { const f32x4 v0 = acc[ai][bj][m][0], v1 = acc[ai][bj][m][1];
;                     u32x4 w; w.x = cvt_pk_bf16(v0[0], v0[1]); w.y = cvt_pk_bf16(v0[2], v0[3]); w.z = cvt_pk_bf16(v1[0], v1[1]); w.w = cvt_pk_bf16(v1[2], v1[3]);
;                     *(u32x4*)(rowp + bj * HALF) = w; } }
.LBB0_186:
	s_branch .Lbp_epi
	v_ashrrev_i32_e32 v131, 31, v146
	v_mov_b32_e32 v130, v146
	v_mov_b64_e32 v[134:135], s[86:87]
	v_mad_i64_i32 v[132:133], s[30:31], v184, s51, v[134:135]
	v_lshlrev_b64 v[136:137], 1, v[130:131]
	v_lshl_add_u64 v[156:157], v[132:133], 0, v[136:137]
	v_cvt_pk_bf16_f32 v130, v126, v127
	v_cvt_pk_bf16_f32 v131, v128, v129
	v_cvt_pk_bf16_f32 v132, v122, v123
	v_cvt_pk_bf16_f32 v133, v124, v125
	global_store_dwordx4 v[156:157], v[130:133], off
	s_nop 1
	v_cvt_pk_bf16_f32 v130, v118, v119
	v_cvt_pk_bf16_f32 v131, v120, v121
	v_cvt_pk_bf16_f32 v132, v114, v115
	v_cvt_pk_bf16_f32 v133, v116, v117
	global_store_dwordx4 v[156:157], v[130:133], off offset:256
	s_nop 1
	v_mad_i64_i32 v[130:131], s[30:31], v183, s51, v[134:135]
	v_lshl_add_u64 v[156:157], v[130:131], 0, v[136:137]
	v_cvt_pk_bf16_f32 v130, v110, v111
	v_cvt_pk_bf16_f32 v131, v112, v113
	v_cvt_pk_bf16_f32 v132, v106, v107
	v_cvt_pk_bf16_f32 v133, v108, v109
	global_store_dwordx4 v[156:157], v[130:133], off
	s_nop 1
	v_cvt_pk_bf16_f32 v130, v102, v103
	v_cvt_pk_bf16_f32 v131, v104, v105
	v_cvt_pk_bf16_f32 v132, v98, v99
	v_cvt_pk_bf16_f32 v133, v100, v101
	global_store_dwordx4 v[156:157], v[130:133], off offset:256
	s_nop 1
	v_mad_i64_i32 v[130:131], s[30:31], v182, s51, v[134:135]
	v_lshl_add_u64 v[156:157], v[130:131], 0, v[136:137]
	v_cvt_pk_bf16_f32 v130, v94, v95
	v_cvt_pk_bf16_f32 v131, v96, v97
	v_cvt_pk_bf16_f32 v132, v90, v91
	v_cvt_pk_bf16_f32 v133, v92, v93
	global_store_dwordx4 v[156:157], v[130:133], off
	s_nop 1
	v_cvt_pk_bf16_f32 v130, v86, v87
	v_cvt_pk_bf16_f32 v131, v88, v89
	v_cvt_pk_bf16_f32 v132, v82, v83
	v_cvt_pk_bf16_f32 v133, v84, v85
	global_store_dwordx4 v[156:157], v[130:133], off offset:256
	s_nop 1
	v_mad_i64_i32 v[130:131], s[30:31], v181, s51, v[134:135]
	v_lshl_add_u64 v[156:157], v[130:131], 0, v[136:137]
	v_cvt_pk_bf16_f32 v130, v78, v79
	v_cvt_pk_bf16_f32 v131, v80, v81
	v_cvt_pk_bf16_f32 v132, v74, v75
	v_cvt_pk_bf16_f32 v133, v76, v77
	global_store_dwordx4 v[156:157], v[130:133], off
	s_nop 1
	v_cvt_pk_bf16_f32 v130, v70, v71
	v_cvt_pk_bf16_f32 v131, v72, v73
	v_cvt_pk_bf16_f32 v132, v66, v67
	v_cvt_pk_bf16_f32 v133, v68, v69
	global_store_dwordx4 v[156:157], v[130:133], off offset:256
	s_nop 1
	v_mad_i64_i32 v[130:131], s[30:31], v180, s51, v[134:135]
	v_lshl_add_u64 v[156:157], v[130:131], 0, v[136:137]
	v_cvt_pk_bf16_f32 v130, v62, v63
	v_cvt_pk_bf16_f32 v131, v64, v65
	v_cvt_pk_bf16_f32 v132, v58, v59
	v_cvt_pk_bf16_f32 v133, v60, v61
	global_store_dwordx4 v[156:157], v[130:133], off
	s_nop 1
	v_cvt_pk_bf16_f32 v130, v54, v55
	v_cvt_pk_bf16_f32 v131, v56, v57
	v_cvt_pk_bf16_f32 v132, v50, v51
	v_cvt_pk_bf16_f32 v133, v52, v53
	global_store_dwordx4 v[156:157], v[130:133], off offset:256
	s_nop 1
	v_mad_i64_i32 v[130:131], s[30:31], v179, s51, v[134:135]
	v_lshl_add_u64 v[156:157], v[130:131], 0, v[136:137]
	v_cvt_pk_bf16_f32 v130, v46, v47
	v_cvt_pk_bf16_f32 v131, v48, v49
	v_cvt_pk_bf16_f32 v132, v42, v43
	v_cvt_pk_bf16_f32 v133, v44, v45
	global_store_dwordx4 v[156:157], v[130:133], off
	s_nop 1
	v_cvt_pk_bf16_f32 v130, v38, v39
	v_cvt_pk_bf16_f32 v131, v40, v41
	v_cvt_pk_bf16_f32 v132, v34, v35
	v_cvt_pk_bf16_f32 v133, v36, v37
	global_store_dwordx4 v[156:157], v[130:133], off offset:256
	s_nop 1
	v_mad_i64_i32 v[130:131], s[30:31], v178, s51, v[134:135]
	v_lshl_add_u64 v[156:157], v[130:131], 0, v[136:137]
	v_cvt_pk_bf16_f32 v130, v30, v31
	v_cvt_pk_bf16_f32 v131, v32, v33
	v_cvt_pk_bf16_f32 v132, v26, v27
	v_cvt_pk_bf16_f32 v133, v28, v29
	global_store_dwordx4 v[156:157], v[130:133], off
	s_nop 1
	v_cvt_pk_bf16_f32 v130, v22, v23
	v_cvt_pk_bf16_f32 v131, v24, v25
	v_cvt_pk_bf16_f32 v132, v18, v19
	v_cvt_pk_bf16_f32 v133, v20, v21
	global_store_dwordx4 v[156:157], v[130:133], off offset:256
	s_nop 1
	v_mad_i64_i32 v[130:131], s[30:31], v177, s51, v[134:135]
	v_lshl_add_u64 v[156:157], v[130:131], 0, v[136:137]
	v_cvt_pk_bf16_f32 v130, v14, v15
	v_cvt_pk_bf16_f32 v131, v16, v17
	v_cvt_pk_bf16_f32 v132, v10, v11
	v_cvt_pk_bf16_f32 v133, v12, v13
	global_store_dwordx4 v[156:157], v[130:133], off
	v_cvt_pk_bf16_f32 v134, v6, v7
	v_cvt_pk_bf16_f32 v135, v8, v9
	v_cvt_pk_bf16_f32 v136, v2, v3
	v_cvt_pk_bf16_f32 v137, v4, v5
	s_cbranch_execnz .LBB0_185
